# v52 plus non-temporal hint on the read-once Q tile loads of each prompt-attention unit
# speedup vs baseline: 1.0006x; 1.0006x over previous
.LBB0_1066:
	s_or_b64 exec, exec, s[4:5]
	s_ashr_i32 s8, s18, 6
	s_ashr_i32 s4, s19, 7
	s_mul_i32 s24, s8, 0x2400
	s_sub_i32 s7, 7, s4
	s_and_b32 s9, s8, 3
	s_lshl_b32 s5, s19, 9
	s_add_i32 s24, s24, 0
	s_and_b32 s23, s5, 0xf800
	s_lshl_b32 s19, s7, 8
	s_lshl_b32 s5, s9, 5
	s_add_i32 s24, s24, 0x12800
	v_and_b32_e32 v1, 31, v0
	s_or_b32 s41, s5, s19
	v_mov_b32_e32 v3, s24
	s_movk_i32 s24, 0x90
	v_mad_u32_u24 v3, v1, s24, v3
	s_add_i32 s24, s41, s23
	v_or_b32_e32 v160, s24, v1
	v_mov_b64_e32 v[4:5], s[44:45]
	s_ashr_i32 s22, s18, 8
	s_or_b32 s19, s41, 0x80
	v_mad_u64_u32 v[6:7], s[24:25], v160, s3, v[4:5]
	s_lshl_b32 s24, s22, 6
	s_add_i32 s36, s19, s23
	s_lshl_b32 s92, s6, 8
	s_ashr_i32 s25, s24, 31
	v_or_b32_e32 v178, s36, v1
	v_bfe_u32 v2, v0, 5, 1
	v_lshl_add_u64 v[6:7], v[6:7], 0, s[92:93]
	s_lshl_b64 s[24:25], s[24:25], 1
	v_mad_u64_u32 v[4:5], s[36:37], v178, s3, v[4:5]
	v_lshlrev_b32_e32 v180, 4, v2
	v_lshl_add_u64 v[6:7], v[6:7], 0, s[24:25]
	v_mov_b32_e32 v181, v161
	v_lshl_add_u64 v[4:5], v[4:5], 0, s[92:93]
	v_lshl_add_u64 v[6:7], v[6:7], 0, v[180:181]
	v_lshl_add_u64 v[4:5], v[4:5], 0, s[24:25]
	v_lshl_add_u64 v[10:11], v[4:5], 0, v[180:181]
	v_add_co_u32_e32 v4, vcc, s72, v6
	s_mov_b64 s[52:53], 0x1000
	s_nop 0
	v_addc_co_u32_e32 v5, vcc, 0, v7, vcc
	v_lshl_add_u64 v[8:9], v[6:7], 0, s[52:53]
	global_load_dwordx4 v[32:35], v[4:5], off nt
	v_add_u32_e32 v195, v3, v180
	v_lshl_add_u64 v[12:13], v[10:11], 0, s[52:53]
	v_add_co_u32_e32 v14, vcc, s72, v10
	s_nop 1
	v_addc_co_u32_e32 v15, vcc, 0, v11, vcc
	global_load_dwordx4 v[36:39], v[14:15], off nt
	global_load_dwordx4 v[40:43], v[8:9], off offset:32 nt
	global_load_dwordx4 v[44:47], v[12:13], off offset:32 nt
	global_load_dwordx4 v[48:51], v[8:9], off offset:64 nt
	global_load_dwordx4 v[52:55], v[12:13], off offset:64 nt
	global_load_dwordx4 v[56:59], v[8:9], off offset:96 nt
	global_load_dwordx4 v[60:63], v[12:13], off offset:96 nt
	s_add_u32 s24, s44, s92
	v_lshlrev_b32_e32 v3, 4, v0
	s_addc_u32 s25, s45, 0
	v_and_b32_e32 v20, 0xf0, v3
	v_mov_b32_e32 v21, v161
	v_ashrrev_i32_e32 v184, 4, v0
	v_lshl_add_u64 v[182:183], s[24:25], 0, v[20:21]
	v_add_u32_e32 v3, s23, v184
	v_add_u32_e32 v250, 0, v20
	s_or_b32 s36, s23, 64
	v_mov_b32_e32 v249, 0x5800
	v_mov_b32_e32 v240, 0x3d800000
	v_mov_b32_e32 v192, 0x358637bd
	s_cmp_lt_i32 s8, 4
	v_mad_i64_i32 v[4:5], s[24:25], v3, s3, v[182:183]
	v_add_u32_e32 v3, 0x200, v0
	v_ashrrev_i32_e32 v186, 4, v3
	v_add_co_u32_e32 v8, vcc, s72, v4
	v_add_u32_e32 v3, s23, v186
	s_nop 0
	v_addc_co_u32_e32 v9, vcc, 0, v5, vcc
	v_mad_i64_i32 v[12:13], s[24:25], v3, s3, v[182:183]
	global_load_dwordx4 v[4:7], v[8:9], off offset:1024
	s_nop 0
	global_load_dwordx4 v[8:11], v[8:9], off offset:2048
	v_add_co_u32_e32 v16, vcc, s72, v12
	s_movk_i32 s24, 0x110
	s_nop 0
	v_addc_co_u32_e32 v17, vcc, 0, v13, vcc
	global_load_dwordx4 v[12:15], v[16:17], off offset:1024
	s_nop 0
	global_load_dwordx4 v[16:19], v[16:17], off offset:2048
	v_mul_lo_u32 v251, v184, s24
	s_movk_i32 s25, 0x140
	v_add_u32_e32 v3, v250, v251
	v_mul_lo_u32 v252, v184, s25
	v_mul_lo_u32 v253, v186, s24
	v_mul_lo_u32 v236, v186, s25
	s_waitcnt vmcnt(4)
	ds_write_b128 v195, v[32:35]
	ds_write_b128 v195, v[36:39] offset:4608
	ds_write_b128 v195, v[40:43] offset:32
	ds_write_b128 v195, v[44:47] offset:4640
	ds_write_b128 v195, v[48:51] offset:64
	ds_write_b128 v195, v[52:55] offset:4672
	ds_write_b128 v195, v[56:59] offset:96
	ds_write_b128 v195, v[60:63] offset:4704
	s_waitcnt vmcnt(3)
	ds_write_b128 v3, v[4:7]
	v_add_u32_e32 v3, v250, v252
	s_waitcnt vmcnt(2)
	ds_write_b128 v3, v[8:11] offset:17408
	v_add_u32_e32 v3, v250, v253
	s_waitcnt vmcnt(1)
	ds_write_b128 v3, v[12:15]
	v_add_u32_e32 v3, v250, v236
	s_waitcnt vmcnt(0)
	ds_write_b128 v3, v[16:19] offset:17408
	v_add_u32_e32 v3, s36, v184
	v_mad_i64_i32 v[4:5], s[24:25], v3, s3, v[182:183]
	v_add_co_u32_e32 v4, vcc, s72, v4
	v_add_u32_e32 v3, s36, v186
	s_nop 0
	v_addc_co_u32_e32 v5, vcc, 0, v5, vcc
	global_load_dwordx4 v[162:165], v[4:5], off offset:1024
	global_load_dwordx4 v[166:169], v[4:5], off offset:2048
	v_mad_i64_i32 v[4:5], s[24:25], v3, s3, v[182:183]
	v_add_co_u32_e32 v4, vcc, 0x1000, v4
	s_nop 1
	v_addc_co_u32_e32 v5, vcc, 0, v5, vcc
	global_load_dwordx4 v[170:173], v[4:5], off offset:1024
	global_load_dwordx4 v[174:177], v[4:5], off offset:2048
	s_mov_b64 s[24:25], 0x38000
	v_lshl_add_u64 v[8:9], v[4:5], 0, s[24:25]
	s_mov_b64 s[24:25], 0x70000
	v_lshl_add_u64 v[10:11], v[4:5], 0, s[24:25]
	global_load_dword v239, v[8:9], off offset:1024
	global_load_dword v239, v[8:9], off offset:2048
	global_load_dword v239, v[10:11], off offset:1024
	global_load_dword v239, v[10:11], off offset:2048
	s_waitcnt lgkmcnt(0)
	s_barrier
	s_cbranch_scc1 .LBB0_1068
	s_setprio 1
